# v052 + attention: next K/V tile LDS-DMA pieces spread over head/step1/step2/step3 instead of all four behind the tile barrier
# speedup vs baseline: 1.0408x; 1.0017x over previous
; #define ATT_LAS __attribute__((address_space(3)))
; #define ATT_STAGE(t, buf) do { _Pragma("unroll") for (int i_ = 0; i_ < 2; ++i_) { \
;         glds16(Kt + (size_t)(t) * 131072, ksrc[i_], (unsigned)__builtin_amdgcn_readfirstlane(ldsb + KBUF + (buf) * 16384 + (w * 2 + i_) * 1024)); \
;         glds16(Vt + (size_t)(t) * 131072, vsrc[i_], (unsigned)__builtin_amdgcn_readfirstlane(ldsb + VBUF + (buf) * 16384 + (w * 2 + i_) * 1024)); } } while (0)
; __device__ __forceinline__ void attn_unit(ATT_LAS unsigned char* lds, const bf16_t* Qg, const bf16_t* Kg, const bf16_t* Vg, bf16_t* Og, int b, int head, int qb, float lam, const float* subg) {
;     ...
;     for (int t = 0; t < NT; ++t) {
;         const int buf = t & 1;
;         if (t + 1 < NT) ATT_STAGE(t + 1, buf ^ 1);
;         const int kvrel = 64 * t - q0 - 32 * wq;
;         if (kvrel <= 31) {
;             const ATT_LAS unsigned char* kb = lds + KBUF + buf * 16384;
;             const ATT_LAS unsigned char* vb = lds + VBUF + buf * 16384;
;             tile_body(kvrel + 63 > 0, kb, vb, qbase, kaddr, vaddr, O1, O2, m1, m2, l1, l2, kvrel, r, h, wsf);
;         }
;         asm volatile("s_waitcnt vmcnt(0)" ::: "memory"); __syncthreads();
.Ldma_skip:
	s_cmp_ge_u32 s79, s76
	s_cbranch_scc1 .Ldma_k2
	s_and_b32 vcc_lo, s79, 1
	s_lshl_b32 vcc_lo, vcc_lo, 14
	s_add_i32 vcc_lo, vcc_lo, s77
	s_add_i32 vcc_lo, vcc_lo, 0x8000
	s_mov_b32 m0, vcc_lo
	s_nop 0
	global_load_lds_dwordx4 v199, s[94:95]
.Ldma_k2:
	s_cmp_ge_u32 s79, s76
	s_cbranch_scc1 .Ldma_k3
	s_and_b32 vcc_lo, s79, 1
	s_lshl_b32 vcc_lo, vcc_lo, 14
	s_add_i32 vcc_lo, vcc_lo, s50
	s_mov_b32 m0, vcc_lo
	s_nop 0
	global_load_lds_dwordx4 v200, s[92:93]
.Ldma_k3:
	s_cmp_ge_u32 s79, s76
	s_cbranch_scc1 .Ldma_k4
	s_and_b32 vcc_lo, s79, 1
	s_lshl_b32 vcc_lo, vcc_lo, 14
	s_add_i32 vcc_lo, vcc_lo, s50
	s_add_i32 vcc_lo, vcc_lo, 0x8000
	s_mov_b32 m0, vcc_lo
	s_nop 0
	global_load_lds_dwordx4 v201, s[94:95]
.Ldma_k4:
	s_branch .LBB0_288

; #define ATT_LAS __attribute__((address_space(3)))
; #define ATT_STAGE(t, buf) do { _Pragma("unroll") for (int i_ = 0; i_ < 2; ++i_) { \
;         glds16(Kt + (size_t)(t) * 131072, ksrc[i_], (unsigned)__builtin_amdgcn_readfirstlane(ldsb + KBUF + (buf) * 16384 + (w * 2 + i_) * 1024)); \
;         glds16(Vt + (size_t)(t) * 131072, vsrc[i_], (unsigned)__builtin_amdgcn_readfirstlane(ldsb + VBUF + (buf) * 16384 + (w * 2 + i_) * 1024)); } } while (0)
; __device__ __forceinline__ void apply_mask(bool MASK, f32x16& s0, int kvr, int r, int h) {
;     if (MASK) {
;         asm volatile("" ::: "memory");
;         const int d = r - 4 * h - kvr;
; #pragma unroll
;         for (int i = 0; i < 16; ++i) { if (((i & 3) + 8 * (i >> 2)) > d) s0[i] = -INFINITY; }
;     }
; __device__ __forceinline__ void attn_unit(ATT_LAS unsigned char* lds, const bf16_t* Qg, const bf16_t* Kg, const bf16_t* Vg, bf16_t* Og, int b, int head, int qb, float lam, const float* subg) {
;     ...
;     for (int t = 0; t < NT; ++t) {
;         const int buf = t & 1;
;         if (t + 1 < NT) ATT_STAGE(t + 1, buf ^ 1);
;         const int kvrel = 64 * t - q0 - 32 * wq;
;         if (kvrel <= 31) {
;             const ATT_LAS unsigned char* kb = lds + KBUF + buf * 16384;
;             const ATT_LAS unsigned char* vb = lds + VBUF + buf * 16384;
;             tile_body(kvrel + 63 > 0, kb, vb, qbase, kaddr, vaddr, O1, O2, m1, m2, l1, l2, kvrel, r, h, wsf);
.LBB0_289:
	s_and_b32 s4, s79, 1
	s_add_i32 s79, s79, 1
	s_cmp_ge_u32 s79, s76
	s_cbranch_scc1 .LBB0_291
	s_lshl_b32 s5, s4, 14
	s_xor_b32 s5, s5, 0x4000
	s_add_i32 s5, s5, 0
	s_add_i32 s6, s5, 0x8000
	s_add_i32 s7, s5, s77
	s_mov_b32 s8, m0
	s_mov_b32 m0, s7
	s_nop 0
	global_load_lds_dwordx4 v198, s[92:93]
	s_mov_b32 m0, s8
.LBB0_291:
	s_cmp_gt_i32 s80, 31
	s_cbranch_scc1 .Ldma_skip
	s_lshl_b32 s4, s4, 14
	s_add_i32 s81, s4, 0
	v_add_u32_e32 v248, s81, v209
	v_add_u32_e32 v249, s81, v210
	v_add_u32_e32 v250, s81, v211
	v_add_u32_e32 v251, s81, v212
	v_add_u32_e32 v216, s81, v203
	ds_read_b128 v[2:5], v216
	ds_read_b128 v[6:9], v217
	v_add_u32_e32 v218, s81, v204
	v_add_u32_e32 v220, s81, v205
	v_add_u32_e32 v222, s81, v206
	s_waitcnt lgkmcnt(0)
	v_mfma_f32_32x32x16_bf16 v[170:185], v[2:5], v[6:9], 0
	ds_read_b128 v[2:5], v218
	ds_read_b128 v[6:9], v219
	s_cmpk_gt_i32 s80, 0xffc1
	s_cselect_b64 s[36:37], -1, 0
	s_cmpk_lt_i32 s80, 0xffc2
	v_cmp_gt_i32_e32 vcc, 26, v214
	s_waitcnt lgkmcnt(0)
	v_mfma_f32_32x32x16_bf16 v[170:185], v[2:5], v[6:9], v[170:185]
	ds_read_b128 v[2:5], v220
	ds_read_b128 v[6:9], v221
	s_waitcnt lgkmcnt(0)
	v_mfma_f32_32x32x16_bf16 v[170:185], v[2:5], v[6:9], v[170:185]
	ds_read_b128 v[2:5], v222
	ds_read_b128 v[6:9], v223
	s_waitcnt lgkmcnt(0)
	v_mfma_f32_32x32x16_bf16 v[170:185], v[2:5], v[6:9], v[170:185]
	s_cbranch_scc1 .LBB0_296
	v_cmp_gt_i32_e64 s[34:35], 25, v214
	v_cmp_gt_i32_e64 s[28:29], 24, v214
	s_and_b64 s[34:35], vcc, s[34:35]
	v_cmp_gt_i32_e64 s[26:27], 19, v214
	s_and_b64 s[28:29], s[34:35], s[28:29]
	v_cmp_gt_i32_e64 s[24:25], 18, v214
	s_and_b64 s[26:27], s[28:29], s[26:27]
	v_cmp_gt_i32_e64 s[22:23], 17, v214
	s_and_b64 s[24:25], s[26:27], s[24:25]
	v_cmp_gt_i32_e64 s[20:21], 16, v214
	s_and_b64 s[22:23], s[24:25], s[22:23]
	v_cmp_gt_i32_e64 s[18:19], 11, v214
	s_and_b64 s[20:21], s[22:23], s[20:21]
	v_cmp_gt_i32_e64 s[16:17], 10, v214
	s_and_b64 s[18:19], s[20:21], s[18:19]
	v_cmp_gt_i32_e64 s[14:15], 9, v214
	s_and_b64 s[16:17], s[18:19], s[16:17]
	v_cmp_gt_i32_e64 s[12:13], 8, v214
	s_and_b64 s[14:15], s[16:17], s[14:15]
	v_cmp_gt_i32_e64 s[10:11], 3, v214
	s_and_b64 s[12:13], s[14:15], s[12:13]
	v_cmp_gt_i32_e64 s[8:9], 2, v214
	s_and_b64 s[10:11], s[12:13], s[10:11]
	v_cmp_gt_i32_e64 s[6:7], 1, v214
	s_and_b64 s[8:9], s[10:11], s[8:9]
	v_cmp_gt_i32_e64 s[4:5], 0, v214
	s_and_b64 s[6:7], s[8:9], s[6:7]
	s_and_b64 s[4:5], s[6:7], s[4:5]
	v_cndmask_b32_e64 v183, v183, v17, s[34:35]
	v_cndmask_b32_e64 v182, v182, v17, s[28:29]
	v_cndmask_b32_e64 v181, v181, v17, s[26:27]
	v_cndmask_b32_e64 v180, v180, v17, s[24:25]
	v_cndmask_b32_e64 v179, v179, v17, s[22:23]
	v_cndmask_b32_e64 v178, v178, v17, s[20:21]
	v_cndmask_b32_e64 v177, v177, v17, s[18:19]
	v_cndmask_b32_e64 v176, v176, v17, s[16:17]
	v_cndmask_b32_e64 v175, v175, v17, s[14:15]
	v_cndmask_b32_e64 v174, v174, v17, s[12:13]
	v_cndmask_b32_e64 v173, v173, v17, s[10:11]
	v_cndmask_b32_e64 v172, v172, v17, s[8:9]
	v_cndmask_b32_e64 v171, v171, v17, s[6:7]
	v_cndmask_b32_e64 v170, v170, v17, s[4:5]
	v_cndmask_b32_e32 v184, v184, v17, vcc
	v_cmp_gt_i32_e32 vcc, 27, v214
	s_and_saveexec_b64 s[4:5], vcc
	v_mov_b32_e32 v185, s31
	s_or_b64 exec, exec, s[4:5]
